# adds ln1 wave sums via permlane/DPP instead of ds_bpermute chains
# speedup vs baseline: 1.0066x; 1.0021x over previous
.LBB0_589:
	v_add_u32_e32 v0, 0xfffff000, v18
	v_lshrrev_b32_e32 v0, 12, v0
	v_lshl_add_u64 v[74:75], s[8:9], 0, v[32:33]
	v_add_u32_e32 v19, 1, v0
	v_add_co_u32_e32 v0, vcc, 0x1874b000, v74
	v_mov_b64_e32 v[44:45], s[12:13]
	s_nop 0
	v_addc_co_u32_e32 v1, vcc, 0, v75, vcc
	v_cmp_lt_i32_e32 vcc, s18, v18
	v_lshl_add_u64 v[110:111], s[8:9], 0, v[34:35]
	v_mov_b32_e32 v37, v16
	v_cndmask_b32_e32 v19, 0, v19, vcc
	v_add_u32_e32 v19, s60, v19
	v_mad_u64_u32 v[44:45], s[16:17], v19, s41, v[44:45]
	s_mov_b64 s[16:17], 0x4000
	s_nop 0
	v_lshl_add_u64 v[72:73], v[44:45], 0, s[16:17]
	s_mov_b64 s[16:17], 0x8000
	v_lshl_add_u64 v[52:53], v[44:45], 0, s[16:17]
	s_mov_b64 s[16:17], 0x6000
	v_lshl_add_u64 v[54:55], v[44:45], 0, s[16:17]
	s_mov_b32 s16, 0x1274b000
	v_add_co_u32_e32 v46, vcc, s16, v110
	v_lshl_add_u64 v[44:45], v[110:111], 0, s[20:21]
	s_nop 0
	v_addc_co_u32_e32 v47, vcc, 0, v111, vcc
	global_load_dwordx4 v[12:15], v[0:1], off offset:512
	global_load_dwordx4 v[8:11], v[0:1], off offset:1536
	global_load_dwordx4 v[4:7], v[0:1], off offset:2560
	s_nop 0
	global_load_dwordx4 v[0:3], v[0:1], off offset:3584
	s_nop 0
	global_load_dwordx4 v[48:51], v[46:47], off offset:512
	global_load_dwordx4 v[56:59], v[44:45], off offset:16
	v_lshl_add_u64 v[44:45], v[72:73], 0, v[36:37]
	global_load_dwordx4 v[60:63], v[44:45], off
	global_load_dwordx4 v[64:67], v[44:45], off offset:16
	s_mov_b64 s[16:17], 0x1274ba00
	v_lshl_add_u64 v[44:45], v[110:111], 0, s[16:17]
	v_mov_b32_e32 v39, v16
	s_mov_b64 s[16:17], 0x1274c200
	global_load_dwordx4 v[68:71], v[46:47], off offset:2560
	global_load_dwordx4 v[82:85], v[44:45], off offset:16
	v_lshl_add_u64 v[44:45], v[72:73], 0, v[38:39]
	v_lshl_add_u64 v[98:99], v[110:111], 0, s[16:17]
	s_mov_b32 s16, 0x1274c000
	global_load_dwordx4 v[86:89], v[44:45], off
	global_load_dwordx4 v[90:93], v[44:45], off offset:16
	v_add_co_u32_e32 v44, vcc, s16, v110
	v_mov_b32_e32 v41, v16
	s_mov_b64 s[16:17], 0x1274ca00
	v_mov_b32_e32 v43, v16
	v_addc_co_u32_e32 v45, vcc, 0, v111, vcc
	v_lshl_add_u64 v[106:107], v[72:73], 0, v[40:41]
	v_lshl_add_u64 v[114:115], v[110:111], 0, s[16:17]
	v_lshl_add_u64 v[72:73], v[72:73], 0, v[42:43]
	global_load_dwordx4 v[94:97], v[44:45], off offset:512
	s_nop 0
	global_load_dwordx4 v[98:101], v[98:99], off offset:16
	s_nop 0
	global_load_dwordx4 v[102:105], v[106:107], off
	s_nop 0
	global_load_dwordx4 v[106:109], v[106:107], off offset:16
	s_nop 0
	global_load_dwordx4 v[110:113], v[44:45], off offset:2560
	s_nop 0
	global_load_dwordx4 v[114:117], v[114:115], off offset:16
	s_nop 0
	global_load_dwordx4 v[118:121], v[72:73], off
	global_load_dwordx4 v[122:125], v[72:73], off offset:16
	v_lshl_add_u64 v[138:139], v[54:55], 0, v[36:37]
	s_mov_b32 s16, 0x1b74b000
	v_add_u32_e32 v18, s72, v18
	v_lshl_add_u64 v[32:33], v[32:33], 0, s[0:1]
	v_lshl_add_u64 v[34:35], v[34:35], 0, s[70:71]
	s_waitcnt vmcnt(0)
	v_lshlrev_b32_e32 v134, 16, v14
	v_and_b32_e32 v135, 0xffff0000, v14
	v_lshlrev_b32_e32 v14, 16, v15
	v_and_b32_e32 v15, 0xffff0000, v15
	v_and_b32_e32 v73, 0xffff0000, v2
	v_lshlrev_b32_e32 v72, 16, v2
	v_pk_mul_f32 v[14:15], v[66:67], v[14:15]
	v_pk_mul_f32 v[64:65], v[64:65], v[134:135]
	v_pk_fma_f32 v[58:59], v[58:59], s[86:87], v[14:15] op_sel_hi:[1,0,1]
	v_lshlrev_b32_e32 v14, 16, v12
	v_and_b32_e32 v15, 0xffff0000, v12
	v_pk_mul_f32 v[14:15], v[60:61], v[14:15]
	v_pk_fma_f32 v[56:57], v[56:57], s[86:87], v[64:65] op_sel_hi:[1,0,1]
	v_pk_fma_f32 v[66:67], v[48:49], s[86:87], v[14:15] op_sel_hi:[1,0,1]
	v_lshl_add_u64 v[64:65], v[52:53], 0, v[38:39]
	v_add_f32_e32 v12, 0, v66
	v_add_f32_e32 v14, v67, v12
	v_lshlrev_b32_e32 v12, 16, v13
	v_and_b32_e32 v13, 0xffff0000, v13
	v_pk_mul_f32 v[12:13], v[62:63], v[12:13]
	v_lshl_add_u64 v[60:61], v[54:55], 0, v[38:39]
	v_pk_fma_f32 v[62:63], v[50:51], s[86:87], v[12:13] op_sel_hi:[1,0,1]
	v_pk_mul_f32 v[72:73], v[122:123], v[72:73]
	v_add_f32_e32 v12, v62, v14
	v_add_f32_e32 v12, v63, v12
	v_add_f32_e32 v12, v56, v12
	v_pk_fma_f32 v[142:143], v[114:115], s[86:87], v[72:73] op_sel_hi:[1,0,1]
	v_and_b32_e32 v73, 0xffff0000, v3
	v_lshlrev_b32_e32 v72, 16, v3
	v_add_f32_e32 v12, v57, v12
	v_pk_mul_f32 v[2:3], v[124:125], v[72:73]
	v_lshl_add_u64 v[72:73], v[52:53], 0, v[36:37]
	v_add_f32_e32 v12, v58, v12
	v_pk_fma_f32 v[2:3], v[116:117], s[86:87], v[2:3] op_sel_hi:[1,0,1]
	global_load_dwordx4 v[114:117], v[20:21], off
	global_load_dwordx4 v[122:125], v[20:21], off offset:16
	global_load_dwordx4 v[126:129], v[22:23], off
	global_load_dwordx4 v[130:133], v[22:23], off offset:16
	v_add_f32_e32 v19, v59, v12
	global_load_dwordx4 v[12:15], v[72:73], off offset:16
	global_load_dwordx4 v[48:51], v[72:73], off
	global_load_dwordx4 v[134:137], v[138:139], off offset:16
	s_nop 0
	global_load_dwordx4 v[138:141], v[138:139], off
	s_waitcnt vmcnt(3)
	v_pk_add_f32 v[150:151], v[14:15], 1.0 op_sel_hi:[1,0]
	v_lshlrev_b32_e32 v14, 16, v8
	v_and_b32_e32 v15, 0xffff0000, v8
	v_pk_mul_f32 v[14:15], v[86:87], v[14:15]
	v_pk_add_f32 v[148:149], v[12:13], 1.0 op_sel_hi:[1,0]
	v_pk_fma_f32 v[14:15], v[68:69], s[86:87], v[14:15] op_sel_hi:[1,0,1]
	v_lshlrev_b32_e32 v12, 16, v10
	v_add_f32_e32 v8, v14, v19
	v_add_f32_e32 v19, v15, v8
	v_lshlrev_b32_e32 v8, 16, v9
	v_and_b32_e32 v9, 0xffff0000, v9
	v_pk_mul_f32 v[8:9], v[88:89], v[8:9]
	v_and_b32_e32 v13, 0xffff0000, v10
	v_pk_fma_f32 v[8:9], v[70:71], s[86:87], v[8:9] op_sel_hi:[1,0,1]
	v_pk_mul_f32 v[12:13], v[90:91], v[12:13]
	v_add_f32_e32 v19, v8, v19
	v_pk_fma_f32 v[12:13], v[82:83], s[86:87], v[12:13] op_sel_hi:[1,0,1]
	v_lshlrev_b32_e32 v10, 16, v11
	v_and_b32_e32 v11, 0xffff0000, v11
	v_add_f32_e32 v19, v9, v19
	v_lshlrev_b32_e32 v68, 16, v6
	v_and_b32_e32 v69, 0xffff0000, v6
	v_lshlrev_b32_e32 v6, 16, v7
	v_and_b32_e32 v7, 0xffff0000, v7
	v_pk_mul_f32 v[10:11], v[92:93], v[10:11]
	v_add_f32_e32 v19, v12, v19
	v_pk_mul_f32 v[6:7], v[108:109], v[6:7]
	v_pk_fma_f32 v[10:11], v[84:85], s[86:87], v[10:11] op_sel_hi:[1,0,1]
	v_add_f32_e32 v19, v13, v19
	v_pk_fma_f32 v[84:85], v[100:101], s[86:87], v[6:7] op_sel_hi:[1,0,1]
	v_lshlrev_b32_e32 v6, 16, v4
	v_and_b32_e32 v7, 0xffff0000, v4
	v_add_f32_e32 v19, v10, v19
	v_pk_mul_f32 v[6:7], v[102:103], v[6:7]
	v_add_f32_e32 v19, v11, v19
	v_pk_fma_f32 v[86:87], v[94:95], s[86:87], v[6:7] op_sel_hi:[1,0,1]
	v_pk_mul_f32 v[68:69], v[106:107], v[68:69]
	v_add_f32_e32 v4, v86, v19
	v_add_f32_e32 v6, v87, v4
	v_lshlrev_b32_e32 v4, 16, v5
	v_and_b32_e32 v5, 0xffff0000, v5
	v_pk_mul_f32 v[4:5], v[104:105], v[4:5]
	v_pk_fma_f32 v[82:83], v[98:99], s[86:87], v[68:69] op_sel_hi:[1,0,1]
	v_pk_fma_f32 v[88:89], v[96:97], s[86:87], v[4:5] op_sel_hi:[1,0,1]
	s_waitcnt vmcnt(2)
	v_pk_add_f32 v[146:147], v[50:51], 1.0 op_sel_hi:[1,0]
	v_add_f32_e32 v4, v88, v6
	v_add_f32_e32 v4, v89, v4
	v_add_f32_e32 v4, v82, v4
	v_lshl_add_u64 v[50:51], v[52:53], 0, v[40:41]
	v_add_f32_e32 v4, v83, v4
	v_lshl_add_u64 v[6:7], v[52:53], 0, v[42:43]
	v_lshlrev_b32_e32 v52, 16, v0
	v_and_b32_e32 v53, 0xffff0000, v0
	v_add_f32_e32 v4, v84, v4
	v_pk_mul_f32 v[52:53], v[118:119], v[52:53]
	v_add_f32_e32 v19, v85, v4
	v_pk_fma_f32 v[52:53], v[110:111], s[86:87], v[52:53] op_sel_hi:[1,0,1]
	v_pk_add_f32 v[144:145], v[48:49], 1.0 op_sel_hi:[1,0]
	v_add_f32_e32 v0, v52, v19
	v_add_f32_e32 v19, v53, v0
	v_lshlrev_b32_e32 v0, 16, v1
	v_and_b32_e32 v1, 0xffff0000, v1
	v_pk_mul_f32 v[0:1], v[120:121], v[0:1]
	v_lshl_add_u64 v[48:49], v[54:55], 0, v[40:41]
	v_pk_fma_f32 v[0:1], v[112:113], s[86:87], v[0:1] op_sel_hi:[1,0,1]
	v_lshl_add_u64 v[4:5], v[54:55], 0, v[42:43]
	v_add_f32_e32 v19, v0, v19
	v_add_f32_e32 v19, v1, v19
	v_add_f32_e32 v19, v142, v19
	v_add_f32_e32 v19, v143, v19
	v_add_f32_e32 v19, v2, v19
	v_add_f32_e32 v19, v3, v19
	s_waitcnt lgkmcnt(0)
	v_mov_b32_e32 v37, v19
	s_nop 1
	v_permlane32_swap_b32_e32 v37, v19
	v_add_f32_e32 v19, v19, v37
	v_mov_b32_e32 v37, v19
	s_nop 1
	v_permlane16_swap_b32_e32 v37, v19
	v_add_f32_e32 v19, v19, v37
	s_nop 1
	v_add_f32_dpp v19, v19, v19 row_ror:8 row_mask:0xf bank_mask:0xf
	s_nop 1
	v_add_f32_dpp v19, v19, v19 row_ror:4 row_mask:0xf bank_mask:0xf
	s_nop 1
	v_add_f32_dpp v19, v19, v19 row_ror:2 row_mask:0xf bank_mask:0xf
	s_nop 1
	v_add_f32_dpp v19, v19, v19 row_ror:1 row_mask:0xf bank_mask:0xf
	v_mul_f32_e32 v90, 0x3a000000, v19
	v_pk_add_f32 v[92:93], v[66:67], v[90:91] op_sel_hi:[1,0] neg_lo:[0,1] neg_hi:[0,1]
	v_pk_add_f32 v[96:97], v[62:63], v[90:91] op_sel_hi:[1,0] neg_lo:[0,1] neg_hi:[0,1]
	v_pk_mul_f32 v[94:95], v[92:93], v[92:93]
	v_pk_mul_f32 v[98:99], v[96:97], v[96:97]
	v_add_f32_e32 v19, v94, v95
	v_pk_add_f32 v[100:101], v[56:57], v[90:91] op_sel_hi:[1,0] neg_lo:[0,1] neg_hi:[0,1]
	v_add_f32_e32 v19, v98, v19
	v_pk_mul_f32 v[102:103], v[100:101], v[100:101]
	v_add_f32_e32 v19, v99, v19
	v_pk_add_f32 v[104:105], v[58:59], v[90:91] op_sel_hi:[1,0] neg_lo:[0,1] neg_hi:[0,1]
	v_add_f32_e32 v19, v102, v19
	v_pk_mul_f32 v[106:107], v[104:105], v[104:105]
	v_add_f32_e32 v19, v103, v19
	v_pk_add_f32 v[72:73], v[14:15], v[90:91] op_sel_hi:[1,0] neg_lo:[0,1] neg_hi:[0,1]
	v_add_f32_e32 v19, v106, v19
	v_pk_mul_f32 v[108:109], v[72:73], v[72:73]
	v_add_f32_e32 v19, v107, v19
	v_pk_add_f32 v[68:69], v[8:9], v[90:91] op_sel_hi:[1,0] neg_lo:[0,1] neg_hi:[0,1]
	v_add_f32_e32 v19, v108, v19
	v_pk_mul_f32 v[110:111], v[68:69], v[68:69]
	v_add_f32_e32 v19, v109, v19
	v_pk_add_f32 v[70:71], v[12:13], v[90:91] op_sel_hi:[1,0] neg_lo:[0,1] neg_hi:[0,1]
	v_add_f32_e32 v19, v110, v19
	v_pk_mul_f32 v[112:113], v[70:71], v[70:71]
	v_add_f32_e32 v19, v111, v19
	v_pk_add_f32 v[66:67], v[10:11], v[90:91] op_sel_hi:[1,0] neg_lo:[0,1] neg_hi:[0,1]
	v_add_f32_e32 v19, v112, v19
	v_pk_mul_f32 v[118:119], v[66:67], v[66:67]
	v_add_f32_e32 v19, v113, v19
	v_pk_add_f32 v[62:63], v[86:87], v[90:91] op_sel_hi:[1,0] neg_lo:[0,1] neg_hi:[0,1]
	v_add_f32_e32 v19, v118, v19
	v_pk_mul_f32 v[86:87], v[62:63], v[62:63]
	v_add_f32_e32 v19, v119, v19
	v_pk_add_f32 v[56:57], v[88:89], v[90:91] op_sel_hi:[1,0] neg_lo:[0,1] neg_hi:[0,1]
	v_add_f32_e32 v19, v86, v19
	v_pk_mul_f32 v[88:89], v[56:57], v[56:57]
	v_add_f32_e32 v19, v87, v19
	v_pk_add_f32 v[58:59], v[82:83], v[90:91] op_sel_hi:[1,0] neg_lo:[0,1] neg_hi:[0,1]
	v_add_f32_e32 v19, v88, v19
	v_pk_mul_f32 v[82:83], v[58:59], v[58:59]
	v_add_f32_e32 v19, v89, v19
	v_pk_add_f32 v[54:55], v[84:85], v[90:91] op_sel_hi:[1,0] neg_lo:[0,1] neg_hi:[0,1]
	v_add_f32_e32 v19, v82, v19
	v_pk_mul_f32 v[84:85], v[54:55], v[54:55]
	v_add_f32_e32 v19, v83, v19
	v_pk_add_f32 v[14:15], v[52:53], v[90:91] op_sel_hi:[1,0] neg_lo:[0,1] neg_hi:[0,1]
	v_add_f32_e32 v19, v84, v19
	v_pk_mul_f32 v[52:53], v[14:15], v[14:15]
	v_add_f32_e32 v19, v85, v19
	v_pk_add_f32 v[10:11], v[0:1], v[90:91] op_sel_hi:[1,0] neg_lo:[0,1] neg_hi:[0,1]
	v_add_f32_e32 v19, v52, v19
	v_pk_mul_f32 v[0:1], v[10:11], v[10:11]
	v_add_f32_e32 v19, v53, v19
	v_pk_add_f32 v[12:13], v[142:143], v[90:91] op_sel_hi:[1,0] neg_lo:[0,1] neg_hi:[0,1]
	v_add_f32_e32 v0, v0, v19
	v_pk_mul_f32 v[120:121], v[12:13], v[12:13]
	v_add_f32_e32 v0, v1, v0
	v_pk_add_f32 v[8:9], v[2:3], v[90:91] op_sel_hi:[1,0] neg_lo:[0,1] neg_hi:[0,1]
	v_add_f32_e32 v0, v120, v0
	v_pk_mul_f32 v[2:3], v[8:9], v[8:9]
	v_add_f32_e32 v0, v121, v0
	v_add_f32_e32 v0, v2, v0
	v_add_f32_e32 v0, v3, v0
	s_waitcnt lgkmcnt(0)
	v_mov_b32_e32 v1, v0
	s_nop 1
	v_permlane32_swap_b32_e32 v1, v0
	v_add_f32_e32 v0, v0, v1
	v_mov_b32_e32 v1, v0
	s_nop 1
	v_permlane16_swap_b32_e32 v1, v0
	v_add_f32_e32 v0, v0, v1
	s_nop 1
	v_add_f32_dpp v0, v0, v0 row_ror:8 row_mask:0xf bank_mask:0xf
	s_nop 1
	v_add_f32_dpp v0, v0, v0 row_ror:4 row_mask:0xf bank_mask:0xf
	s_nop 1
	v_add_f32_dpp v0, v0, v0 row_ror:2 row_mask:0xf bank_mask:0xf
	s_nop 1
	v_add_f32_dpp v0, v0, v0 row_ror:1 row_mask:0xf bank_mask:0xf
	v_fmamk_f32 v0, v0, 0x3a000000, v186
	v_cmp_gt_f32_e32 vcc, s54, v0
	v_mul_f32_e32 v1, 0x4b800000, v0
	s_nop 0
	v_cndmask_b32_e32 v0, v0, v1, vcc
	v_rsq_f32_e32 v0, v0
	s_nop 0
	v_mul_f32_e32 v1, 0x45800000, v0
	v_cndmask_b32_e32 v52, v0, v1, vcc
	v_pk_mul_f32 v[2:3], v[100:101], v[52:53] op_sel_hi:[1,0]
	v_pk_mul_f32 v[0:1], v[92:93], v[52:53] op_sel_hi:[1,0]
	v_pk_fma_f32 v[82:83], v[122:123], v[2:3], v[130:131]
	v_pk_mul_f32 v[2:3], v[96:97], v[52:53] op_sel_hi:[1,0]
	v_pk_fma_f32 v[0:1], v[114:115], v[0:1], v[126:127]
	v_pk_fma_f32 v[2:3], v[116:117], v[2:3], v[128:129]
	v_pk_mul_f32 v[84:85], v[104:105], v[52:53] op_sel_hi:[1,0]
	v_add_co_u32_e32 v74, vcc, s16, v74
	v_pk_fma_f32 v[84:85], v[124:125], v[84:85], v[132:133]
	global_store_dwordx4 v[46:47], v[0:3], off offset:512
	global_store_dwordx4 v[46:47], v[82:85], off offset:528
	v_addc_co_u32_e32 v75, vcc, 0, v75, vcc
	s_waitcnt vmcnt(2)
	v_pk_fma_f32 v[0:1], v[144:145], v[0:1], v[138:139]
	v_pk_fma_f32 v[2:3], v[146:147], v[2:3], v[140:141]
	v_cvt_pk_bf16_f32 v0, v0, v1
	v_cvt_pk_bf16_f32 v1, v2, v3
	v_pk_fma_f32 v[2:3], v[148:149], v[82:83], v[134:135]
	v_pk_fma_f32 v[82:83], v[150:151], v[84:85], v[136:137]
	v_cvt_pk_bf16_f32 v2, v2, v3
	v_cvt_pk_bf16_f32 v3, v82, v83
	global_store_dwordx4 v[74:75], v[0:3], off offset:512
	global_load_dwordx4 v[0:3], v[20:21], off offset:2064
	s_nop 0
	global_load_dwordx4 v[82:85], v[20:21], off offset:2048
	global_load_dwordx4 v[86:89], v[22:23], off offset:2064
	global_load_dwordx4 v[90:93], v[22:23], off offset:2048
	v_pk_mul_f32 v[72:73], v[72:73], v[52:53] op_sel_hi:[1,0]
	v_pk_mul_f32 v[68:69], v[68:69], v[52:53] op_sel_hi:[1,0]
	v_pk_mul_f32 v[70:71], v[70:71], v[52:53] op_sel_hi:[1,0]
	v_pk_mul_f32 v[66:67], v[66:67], v[52:53] op_sel_hi:[1,0]
	v_pk_mul_f32 v[14:15], v[14:15], v[52:53] op_sel_hi:[1,0]
	v_pk_mul_f32 v[10:11], v[10:11], v[52:53] op_sel_hi:[1,0]
	v_pk_mul_f32 v[12:13], v[12:13], v[52:53] op_sel_hi:[1,0]
	v_pk_mul_f32 v[8:9], v[8:9], v[52:53] op_sel_hi:[1,0]
	s_movk_i32 s16, 0x2fff
	v_cmp_lt_i32_e32 vcc, s16, v18
	s_or_b64 s[14:15], vcc, s[14:15]
	s_waitcnt vmcnt(1)
	v_pk_fma_f32 v[0:1], v[0:1], v[70:71], v[86:87]
	s_waitcnt vmcnt(0)
	v_pk_fma_f32 v[82:83], v[82:83], v[72:73], v[90:91]
	v_pk_fma_f32 v[84:85], v[84:85], v[68:69], v[92:93]
	v_pk_fma_f32 v[2:3], v[2:3], v[66:67], v[88:89]
	global_store_dwordx4 v[46:47], v[82:85], off offset:2560
	global_store_dwordx4 v[46:47], v[0:3], off offset:2576
	global_load_dwordx4 v[66:69], v[64:65], off offset:16
	global_load_dwordx4 v[70:73], v[64:65], off
	global_load_dwordx4 v[86:89], v[60:61], off offset:16
	global_load_dwordx4 v[90:93], v[60:61], off
	s_waitcnt vmcnt(2)
	v_pk_add_f32 v[46:47], v[70:71], 1.0 op_sel_hi:[1,0]
	s_waitcnt vmcnt(0)
	v_pk_fma_f32 v[46:47], v[46:47], v[82:83], v[90:91]
	s_nop 0
	v_cvt_pk_bf16_f32 v64, v46, v47
	v_pk_add_f32 v[46:47], v[72:73], 1.0 op_sel_hi:[1,0]
	s_nop 0
	v_pk_fma_f32 v[46:47], v[46:47], v[84:85], v[92:93]
	s_nop 0
	v_cvt_pk_bf16_f32 v65, v46, v47
	v_pk_add_f32 v[46:47], v[66:67], 1.0 op_sel_hi:[1,0]
	s_nop 0
	v_pk_fma_f32 v[0:1], v[46:47], v[0:1], v[86:87]
	v_pk_mul_f32 v[46:47], v[62:63], v[52:53] op_sel_hi:[1,0]
	v_cvt_pk_bf16_f32 v66, v0, v1
	v_pk_add_f32 v[0:1], v[68:69], 1.0 op_sel_hi:[1,0]
	s_nop 0
	v_pk_fma_f32 v[0:1], v[0:1], v[2:3], v[88:89]
	s_nop 0
	v_cvt_pk_bf16_f32 v67, v0, v1
	global_store_dwordx4 v[74:75], v[64:67], off offset:1536
	global_load_dwordx4 v[0:3], v[24:25], off offset:16
	s_nop 0
	global_load_dwordx4 v[64:67], v[24:25], off
	global_load_dwordx4 v[68:71], v[26:27], off offset:16
	global_load_dwordx4 v[82:85], v[26:27], off
	s_waitcnt vmcnt(0)
	v_pk_fma_f32 v[60:61], v[64:65], v[46:47], v[82:83]
	v_pk_mul_f32 v[46:47], v[58:59], v[52:53] op_sel_hi:[1,0]
	s_nop 0
	v_pk_fma_f32 v[0:1], v[0:1], v[46:47], v[68:69]
	v_pk_mul_f32 v[46:47], v[56:57], v[52:53] op_sel_hi:[1,0]
	s_nop 0
	v_pk_fma_f32 v[62:63], v[66:67], v[46:47], v[84:85]
	v_pk_mul_f32 v[46:47], v[54:55], v[52:53] op_sel_hi:[1,0]
	s_nop 0
	v_pk_fma_f32 v[2:3], v[2:3], v[46:47], v[70:71]
	global_store_dwordx4 v[44:45], v[60:63], off offset:512
	global_store_dwordx4 v[44:45], v[0:3], off offset:528
	global_load_dwordx4 v[54:57], v[50:51], off offset:16
	global_load_dwordx4 v[64:67], v[50:51], off
	global_load_dwordx4 v[68:71], v[48:49], off offset:16
	s_nop 0
	global_load_dwordx4 v[46:49], v[48:49], off
	s_waitcnt vmcnt(2)
	v_pk_add_f32 v[50:51], v[64:65], 1.0 op_sel_hi:[1,0]
	s_waitcnt vmcnt(0)
	v_pk_fma_f32 v[46:47], v[50:51], v[60:61], v[46:47]
	v_pk_add_f32 v[50:51], v[66:67], 1.0 op_sel_hi:[1,0]
	v_cvt_pk_bf16_f32 v46, v46, v47
	v_pk_fma_f32 v[48:49], v[50:51], v[62:63], v[48:49]
	s_nop 0
	v_cvt_pk_bf16_f32 v47, v48, v49
	v_pk_add_f32 v[48:49], v[54:55], 1.0 op_sel_hi:[1,0]
	s_nop 0
	v_pk_fma_f32 v[0:1], v[48:49], v[0:1], v[68:69]
	s_nop 0
	v_cvt_pk_bf16_f32 v48, v0, v1
	v_pk_add_f32 v[0:1], v[56:57], 1.0 op_sel_hi:[1,0]
	s_nop 0
	v_pk_fma_f32 v[0:1], v[0:1], v[2:3], v[70:71]
	s_nop 0
	v_cvt_pk_bf16_f32 v49, v0, v1
	global_store_dwordx4 v[74:75], v[46:49], off offset:2560
	global_load_dwordx4 v[0:3], v[28:29], off offset:16
	s_nop 0
	global_load_dwordx4 v[46:49], v[28:29], off
	global_load_dwordx4 v[54:57], v[30:31], off offset:16
	global_load_dwordx4 v[58:61], v[30:31], off
	s_waitcnt vmcnt(1)
	v_pk_fma_f32 v[0:1], v[0:1], v[12:13], v[54:55]
	s_waitcnt vmcnt(0)
	v_pk_fma_f32 v[46:47], v[46:47], v[14:15], v[58:59]
	v_pk_fma_f32 v[48:49], v[48:49], v[10:11], v[60:61]
	v_pk_fma_f32 v[2:3], v[2:3], v[8:9], v[56:57]
	global_store_dwordx4 v[44:45], v[46:49], off offset:2560
	global_store_dwordx4 v[44:45], v[0:3], off offset:2576
	global_load_dwordx4 v[8:11], v[6:7], off offset:16
	global_load_dwordx4 v[12:15], v[6:7], off
	global_load_dwordx4 v[50:53], v[4:5], off offset:16
	s_nop 0
	global_load_dwordx4 v[4:7], v[4:5], off
	s_waitcnt vmcnt(2)
	v_pk_add_f32 v[12:13], v[12:13], 1.0 op_sel_hi:[1,0]
	s_waitcnt vmcnt(0)
	v_pk_fma_f32 v[4:5], v[12:13], v[46:47], v[4:5]
	v_pk_add_f32 v[12:13], v[14:15], 1.0 op_sel_hi:[1,0]
	v_cvt_pk_bf16_f32 v4, v4, v5
	v_pk_fma_f32 v[6:7], v[12:13], v[48:49], v[6:7]
	s_nop 0
	v_cvt_pk_bf16_f32 v5, v6, v7
	v_pk_add_f32 v[6:7], v[8:9], 1.0 op_sel_hi:[1,0]
	s_nop 0
	v_pk_fma_f32 v[0:1], v[6:7], v[0:1], v[50:51]
	s_nop 0
	v_cvt_pk_bf16_f32 v6, v0, v1
	v_pk_add_f32 v[0:1], v[10:11], 1.0 op_sel_hi:[1,0]
	s_nop 0
	v_pk_fma_f32 v[0:1], v[0:1], v[2:3], v[52:53]
	s_nop 0
	v_cvt_pk_bf16_f32 v7, v0, v1
	global_store_dwordx4 v[74:75], v[4:7], off offset:3584
	s_andn2_b64 exec, exec, s[14:15]
	s_cbranch_execnz .LBB0_589
